# instruction selection in the GEMM tile loop: the 128-instruction accumulator zeroing chain (v_mov_b32 per register) replaced by 63 v_pk_mov_b32 register-pair moves
# baseline (speedup 1.0000x reference)
; template <class Epi, class Sched, bool ALIGN_EPI = false, bool SP2 = false>
; __device__ __forceinline__ void gemm_phase(PG8_LAS unsigned char* lds, const Gemm g, const Sched& S, const Epi& E) {
;     ...
; #pragma unroll
;         for (int a = 0; a < 2; ++a)
; #pragma unroll
;             for (int b = 0; b < 2; ++b)
; #pragma unroll
;                 for (int m = 0; m < 4; ++m)
; #pragma unroll
;                     for (int n = 0; n < 2; ++n) acc[a][b][m][n] = (f32x4){0.f, 0.f, 0.f, 0.f};
;         cur = nxt; cA = nA; cB = nB; ++ui;
.LBB0_153:
	s_add_u32 s12, s12, 0x80
	s_addc_u32 s13, s13, 0
	s_add_u32 s2, s14, 0x100
	v_mov_b32_e32 v2, 0
	s_addc_u32 s11, s15, 0
	s_mov_b32 s14, 0
	v_mov_b32_e32 v3, 0
	v_pk_mov_b32 v[4:5], v[2:3], v[2:3]
	v_pk_mov_b32 v[6:7], v[2:3], v[2:3]
	v_pk_mov_b32 v[8:9], v[2:3], v[2:3]
	v_pk_mov_b32 v[10:11], v[2:3], v[2:3]
	v_pk_mov_b32 v[12:13], v[2:3], v[2:3]
	v_pk_mov_b32 v[14:15], v[2:3], v[2:3]
	v_pk_mov_b32 v[16:17], v[2:3], v[2:3]
	v_pk_mov_b32 v[18:19], v[2:3], v[2:3]
	v_pk_mov_b32 v[20:21], v[2:3], v[2:3]
	v_pk_mov_b32 v[22:23], v[2:3], v[2:3]
	v_pk_mov_b32 v[24:25], v[2:3], v[2:3]
	v_pk_mov_b32 v[26:27], v[2:3], v[2:3]
	v_pk_mov_b32 v[28:29], v[2:3], v[2:3]
	v_pk_mov_b32 v[30:31], v[2:3], v[2:3]
	v_pk_mov_b32 v[32:33], v[2:3], v[2:3]
	v_pk_mov_b32 v[66:67], v[2:3], v[2:3]
	v_pk_mov_b32 v[68:69], v[2:3], v[2:3]
	v_pk_mov_b32 v[70:71], v[2:3], v[2:3]
	v_pk_mov_b32 v[72:73], v[2:3], v[2:3]
	v_pk_mov_b32 v[74:75], v[2:3], v[2:3]
	v_pk_mov_b32 v[76:77], v[2:3], v[2:3]
	v_pk_mov_b32 v[78:79], v[2:3], v[2:3]
	v_pk_mov_b32 v[80:81], v[2:3], v[2:3]
	v_pk_mov_b32 v[82:83], v[2:3], v[2:3]
	v_pk_mov_b32 v[84:85], v[2:3], v[2:3]
	v_pk_mov_b32 v[86:87], v[2:3], v[2:3]
	v_pk_mov_b32 v[88:89], v[2:3], v[2:3]
	v_pk_mov_b32 v[90:91], v[2:3], v[2:3]
	v_pk_mov_b32 v[92:93], v[2:3], v[2:3]
	v_pk_mov_b32 v[94:95], v[2:3], v[2:3]
	v_pk_mov_b32 v[96:97], v[2:3], v[2:3]
	v_pk_mov_b32 v[34:35], v[2:3], v[2:3]
	v_pk_mov_b32 v[36:37], v[2:3], v[2:3]
	v_pk_mov_b32 v[38:39], v[2:3], v[2:3]
	v_pk_mov_b32 v[40:41], v[2:3], v[2:3]
	v_pk_mov_b32 v[42:43], v[2:3], v[2:3]
	v_pk_mov_b32 v[44:45], v[2:3], v[2:3]
	v_pk_mov_b32 v[46:47], v[2:3], v[2:3]
	v_pk_mov_b32 v[48:49], v[2:3], v[2:3]
	v_pk_mov_b32 v[50:51], v[2:3], v[2:3]
	v_pk_mov_b32 v[52:53], v[2:3], v[2:3]
	v_pk_mov_b32 v[54:55], v[2:3], v[2:3]
	v_pk_mov_b32 v[56:57], v[2:3], v[2:3]
	v_pk_mov_b32 v[58:59], v[2:3], v[2:3]
	v_pk_mov_b32 v[60:61], v[2:3], v[2:3]
	v_pk_mov_b32 v[62:63], v[2:3], v[2:3]
	v_pk_mov_b32 v[64:65], v[2:3], v[2:3]
	v_pk_mov_b32 v[98:99], v[2:3], v[2:3]
	v_pk_mov_b32 v[100:101], v[2:3], v[2:3]
	v_pk_mov_b32 v[102:103], v[2:3], v[2:3]
	v_pk_mov_b32 v[104:105], v[2:3], v[2:3]
	v_pk_mov_b32 v[106:107], v[2:3], v[2:3]
	v_pk_mov_b32 v[108:109], v[2:3], v[2:3]
	v_pk_mov_b32 v[110:111], v[2:3], v[2:3]
	v_pk_mov_b32 v[112:113], v[2:3], v[2:3]
	v_pk_mov_b32 v[114:115], v[2:3], v[2:3]
	v_pk_mov_b32 v[116:117], v[2:3], v[2:3]
	v_pk_mov_b32 v[118:119], v[2:3], v[2:3]
	v_pk_mov_b32 v[120:121], v[2:3], v[2:3]
	v_pk_mov_b32 v[122:123], v[2:3], v[2:3]
	v_pk_mov_b32 v[124:125], v[2:3], v[2:3]
	v_pk_mov_b32 v[126:127], v[2:3], v[2:3]
	v_pk_mov_b32 v[128:129], v[2:3], v[2:3]
